# S5 final carry-in chain: all chunk-end loads issued at once (exec-masked slots), one wait per 32 entries instead of 3 round trips per 8
# baseline (speedup 1.0000x reference)
; template <bool FINAL>
; __device__ __forceinline__ void s5_wave(const Params& P, int j, int g, int idx0, int stride, char* ldsw) {
;     ...
;   float hr = 0.f, hi = 0.f;
;   if (FINAL) {
;     const float2* hp = hend + ((size_t)(b * 64) * 32 + g) * 64 + p;
;     int c = 0;
;     for (; c + 8 <= chunk; c += 8) {
;       float2 e[8];
; #pragma unroll
;       for (int q = 0; q < 8; ++q) e[q] = hp[(size_t)(c + q) * 2048];
; #pragma unroll
.LBB0_430:
	s_ashr_i32 s4, s2, 11
	s_lshr_b32 s0, s2, 5
	s_lshl_b32 s1, s4, 3
	s_add_i32 s1, s1, s0
	s_and_b32 s6, s1, 63
	s_ashr_i32 s5, s4, 31
	s_lshl_b64 s[0:1], s[4:5], 12
	s_lshl_b32 s5, s6, 6
	v_readlane_b32 s8, v253, 46
	s_or_b32 s0, s0, s5
	v_readlane_b32 s9, v253, 47
	s_lshl_b32 s4, s4, 6
	s_nop 0
	s_mul_i32 s7, s0, 0xa00
	s_add_u32 s10, s8, s7
	s_addc_u32 s11, s9, 0
	v_lshl_add_u64 v[234:235], v[110:111], 0, s[10:11]
	global_load_dwordx4 v[194:197], v[234:235], off offset:1536
	global_load_dwordx4 v[198:201], v[234:235], off offset:1552
	s_add_u32 s10, s10, 0x14000
	s_addc_u32 s11, s11, 0
	v_lshl_add_u64 v[234:235], v[110:111], 0, s[10:11]
	global_load_dwordx4 v[202:205], v[234:235], off offset:1536
	global_load_dwordx4 v[242:245], v[234:235], off offset:1552
	s_ashr_i32 s5, s4, 31
	s_lshl_b64 s[4:5], s[4:5], 14
	v_mov_b32_e32 v82, 0
	v_mov_b32_e32 v83, 0
	s_cmp_eq_u32 s6, 0
	s_cbranch_scc1 .Ls5f_cdone
	v_readfirstlane_b32 s14, v80
	v_readfirstlane_b32 s15, v81
	v_lshlrev_b32_e32 v109, 3, v48
	s_add_u32 s14, s14, s4
	s_addc_u32 s15, s15, s5
	s_cmp_gt_u32 s6, 0
	s_cselect_b64 exec, -1, 0
	global_load_dwordx2 v[116:117], v109, s[14:15]
	s_mov_b64 exec, -1
	v_add_u32_e32 v109, 0x4000, v109
	s_cmp_gt_u32 s6, 1
	s_cselect_b64 exec, -1, 0
	global_load_dwordx2 v[118:119], v109, s[14:15]
	s_mov_b64 exec, -1
	v_add_u32_e32 v109, 0x4000, v109
	s_cmp_gt_u32 s6, 2
	s_cselect_b64 exec, -1, 0
	global_load_dwordx2 v[120:121], v109, s[14:15]
	s_mov_b64 exec, -1
	v_add_u32_e32 v109, 0x4000, v109
	s_cmp_gt_u32 s6, 3
	s_cselect_b64 exec, -1, 0
	global_load_dwordx2 v[122:123], v109, s[14:15]
	s_mov_b64 exec, -1
	v_add_u32_e32 v109, 0x4000, v109
	s_cmp_gt_u32 s6, 4
	s_cselect_b64 exec, -1, 0
	global_load_dwordx2 v[124:125], v109, s[14:15]
	s_mov_b64 exec, -1
	v_add_u32_e32 v109, 0x4000, v109
	s_cmp_gt_u32 s6, 5
	s_cselect_b64 exec, -1, 0
	global_load_dwordx2 v[126:127], v109, s[14:15]
	s_mov_b64 exec, -1
	v_add_u32_e32 v109, 0x4000, v109
	s_cmp_gt_u32 s6, 6
	s_cselect_b64 exec, -1, 0
	global_load_dwordx2 v[128:129], v109, s[14:15]
	s_mov_b64 exec, -1
	v_add_u32_e32 v109, 0x4000, v109
	s_cmp_gt_u32 s6, 7
	s_cselect_b64 exec, -1, 0
	global_load_dwordx2 v[130:131], v109, s[14:15]
	s_mov_b64 exec, -1
	v_add_u32_e32 v109, 0x4000, v109
	s_cmp_gt_u32 s6, 8
	s_cselect_b64 exec, -1, 0
	global_load_dwordx2 v[132:133], v109, s[14:15]
	s_mov_b64 exec, -1
	v_add_u32_e32 v109, 0x4000, v109
	s_cmp_gt_u32 s6, 9
	s_cselect_b64 exec, -1, 0
	global_load_dwordx2 v[134:135], v109, s[14:15]
	s_mov_b64 exec, -1
	v_add_u32_e32 v109, 0x4000, v109
	s_cmp_gt_u32 s6, 10
	s_cselect_b64 exec, -1, 0
	global_load_dwordx2 v[136:137], v109, s[14:15]
	s_mov_b64 exec, -1
	v_add_u32_e32 v109, 0x4000, v109
	s_cmp_gt_u32 s6, 11
	s_cselect_b64 exec, -1, 0
	global_load_dwordx2 v[138:139], v109, s[14:15]
	s_mov_b64 exec, -1
	v_add_u32_e32 v109, 0x4000, v109
	s_cmp_gt_u32 s6, 12
	s_cselect_b64 exec, -1, 0
	global_load_dwordx2 v[140:141], v109, s[14:15]
	s_mov_b64 exec, -1
	v_add_u32_e32 v109, 0x4000, v109
	s_cmp_gt_u32 s6, 13
	s_cselect_b64 exec, -1, 0
	global_load_dwordx2 v[142:143], v109, s[14:15]
	s_mov_b64 exec, -1
	v_add_u32_e32 v109, 0x4000, v109
	s_cmp_gt_u32 s6, 14
	s_cselect_b64 exec, -1, 0
	global_load_dwordx2 v[144:145], v109, s[14:15]
	s_mov_b64 exec, -1
	v_add_u32_e32 v109, 0x4000, v109
	s_cmp_gt_u32 s6, 15
	s_cselect_b64 exec, -1, 0
	global_load_dwordx2 v[146:147], v109, s[14:15]
	s_mov_b64 exec, -1
	v_add_u32_e32 v109, 0x4000, v109
	s_cmp_gt_u32 s6, 16
	s_cselect_b64 exec, -1, 0
	global_load_dwordx2 v[148:149], v109, s[14:15]
	s_mov_b64 exec, -1
	v_add_u32_e32 v109, 0x4000, v109
	s_cmp_gt_u32 s6, 17
	s_cselect_b64 exec, -1, 0
	global_load_dwordx2 v[150:151], v109, s[14:15]
	s_mov_b64 exec, -1
	v_add_u32_e32 v109, 0x4000, v109
	s_cmp_gt_u32 s6, 18
	s_cselect_b64 exec, -1, 0
	global_load_dwordx2 v[152:153], v109, s[14:15]
	s_mov_b64 exec, -1
	v_add_u32_e32 v109, 0x4000, v109
	s_cmp_gt_u32 s6, 19
	s_cselect_b64 exec, -1, 0
	global_load_dwordx2 v[154:155], v109, s[14:15]
	s_mov_b64 exec, -1
	v_add_u32_e32 v109, 0x4000, v109
	s_cmp_gt_u32 s6, 20
	s_cselect_b64 exec, -1, 0
	global_load_dwordx2 v[156:157], v109, s[14:15]
	s_mov_b64 exec, -1
	v_add_u32_e32 v109, 0x4000, v109
	s_cmp_gt_u32 s6, 21
	s_cselect_b64 exec, -1, 0
	global_load_dwordx2 v[158:159], v109, s[14:15]
	s_mov_b64 exec, -1
	v_add_u32_e32 v109, 0x4000, v109
	s_cmp_gt_u32 s6, 22
	s_cselect_b64 exec, -1, 0
	global_load_dwordx2 v[160:161], v109, s[14:15]
	s_mov_b64 exec, -1
	v_add_u32_e32 v109, 0x4000, v109
	s_cmp_gt_u32 s6, 23
	s_cselect_b64 exec, -1, 0
	global_load_dwordx2 v[162:163], v109, s[14:15]
	s_mov_b64 exec, -1
	v_add_u32_e32 v109, 0x4000, v109
	s_cmp_gt_u32 s6, 24
	s_cselect_b64 exec, -1, 0
	global_load_dwordx2 v[164:165], v109, s[14:15]
	s_mov_b64 exec, -1
	v_add_u32_e32 v109, 0x4000, v109
	s_cmp_gt_u32 s6, 25
	s_cselect_b64 exec, -1, 0
	global_load_dwordx2 v[166:167], v109, s[14:15]
	s_mov_b64 exec, -1
	v_add_u32_e32 v109, 0x4000, v109
	s_cmp_gt_u32 s6, 26
	s_cselect_b64 exec, -1, 0
	global_load_dwordx2 v[168:169], v109, s[14:15]
	s_mov_b64 exec, -1
	v_add_u32_e32 v109, 0x4000, v109
	s_cmp_gt_u32 s6, 27
	s_cselect_b64 exec, -1, 0
	global_load_dwordx2 v[170:171], v109, s[14:15]
	s_mov_b64 exec, -1
	v_add_u32_e32 v109, 0x4000, v109
	s_cmp_gt_u32 s6, 28
	s_cselect_b64 exec, -1, 0
	global_load_dwordx2 v[172:173], v109, s[14:15]
	s_mov_b64 exec, -1
	v_add_u32_e32 v109, 0x4000, v109
	s_cmp_gt_u32 s6, 29
	s_cselect_b64 exec, -1, 0
	global_load_dwordx2 v[174:175], v109, s[14:15]
	s_mov_b64 exec, -1
	v_add_u32_e32 v109, 0x4000, v109
	s_cmp_gt_u32 s6, 30
	s_cselect_b64 exec, -1, 0
	global_load_dwordx2 v[176:177], v109, s[14:15]
	s_mov_b64 exec, -1
	v_add_u32_e32 v109, 0x4000, v109
	s_cmp_gt_u32 s6, 31
	s_cselect_b64 exec, -1, 0
	global_load_dwordx2 v[178:179], v109, s[14:15]
	s_mov_b64 exec, -1
	v_add_u32_e32 v109, 0x4000, v109
	s_waitcnt vmcnt(0)
; template <bool FINAL>
; __device__ __forceinline__ void s5_wave(const Params& P, int j, int g, int idx0, int stride, char* ldsw) {
;     ...
;     for (; c + 8 <= chunk; c += 8) {
;       float2 e[8];
; #pragma unroll
;       for (int q = 0; q < 8; ++q) e[q] = hp[(size_t)(c + q) * 2048];
; #pragma unroll
;       for (int q = 0; q < 8; ++q) {
;         float t_r = pr * hr - pi * hi + e[q].x;
;         float t_i = pr * hi + pi * hr + e[q].y;
;         hr = t_r; hi = t_i;
;       }
;     }
	s_cmp_gt_u32 s6, 0
	s_cselect_b64 exec, -1, 0
	v_fma_f32 v116, v72, v82, v116
	v_fma_f32 v117, v72, v83, v117
	v_fma_f32 v117, v74, v82, v117
	v_fma_f32 v82, -v74, v83, v116
	v_mov_b32_e32 v83, v117
	s_cmp_gt_u32 s6, 1
	s_cselect_b64 exec, -1, 0
	v_fma_f32 v118, v72, v82, v118
	v_fma_f32 v119, v72, v83, v119
	v_fma_f32 v119, v74, v82, v119
	v_fma_f32 v82, -v74, v83, v118
	v_mov_b32_e32 v83, v119
	s_cmp_gt_u32 s6, 2
	s_cselect_b64 exec, -1, 0
	v_fma_f32 v120, v72, v82, v120
	v_fma_f32 v121, v72, v83, v121
	v_fma_f32 v121, v74, v82, v121
	v_fma_f32 v82, -v74, v83, v120
	v_mov_b32_e32 v83, v121
	s_cmp_gt_u32 s6, 3
	s_cselect_b64 exec, -1, 0
	v_fma_f32 v122, v72, v82, v122
	v_fma_f32 v123, v72, v83, v123
	v_fma_f32 v123, v74, v82, v123
	v_fma_f32 v82, -v74, v83, v122
	v_mov_b32_e32 v83, v123
	s_cmp_gt_u32 s6, 4
	s_cselect_b64 exec, -1, 0
	v_fma_f32 v124, v72, v82, v124
	v_fma_f32 v125, v72, v83, v125
	v_fma_f32 v125, v74, v82, v125
	v_fma_f32 v82, -v74, v83, v124
	v_mov_b32_e32 v83, v125
	s_cmp_gt_u32 s6, 5
	s_cselect_b64 exec, -1, 0
	v_fma_f32 v126, v72, v82, v126
	v_fma_f32 v127, v72, v83, v127
	v_fma_f32 v127, v74, v82, v127
	v_fma_f32 v82, -v74, v83, v126
	v_mov_b32_e32 v83, v127
	s_cmp_gt_u32 s6, 6
	s_cselect_b64 exec, -1, 0
	v_fma_f32 v128, v72, v82, v128
	v_fma_f32 v129, v72, v83, v129
	v_fma_f32 v129, v74, v82, v129
	v_fma_f32 v82, -v74, v83, v128
	v_mov_b32_e32 v83, v129
	s_cmp_gt_u32 s6, 7
	s_cselect_b64 exec, -1, 0
	v_fma_f32 v130, v72, v82, v130
	v_fma_f32 v131, v72, v83, v131
	v_fma_f32 v131, v74, v82, v131
	v_fma_f32 v82, -v74, v83, v130
	v_mov_b32_e32 v83, v131
	s_cmp_le_u32 s6, 8
	s_cbranch_scc1 .Ls5f_cdone
	s_cmp_gt_u32 s6, 8
	s_cselect_b64 exec, -1, 0
	v_fma_f32 v132, v72, v82, v132
	v_fma_f32 v133, v72, v83, v133
	v_fma_f32 v133, v74, v82, v133
	v_fma_f32 v82, -v74, v83, v132
	v_mov_b32_e32 v83, v133
	s_cmp_gt_u32 s6, 9
	s_cselect_b64 exec, -1, 0
	v_fma_f32 v134, v72, v82, v134
	v_fma_f32 v135, v72, v83, v135
	v_fma_f32 v135, v74, v82, v135
	v_fma_f32 v82, -v74, v83, v134
	v_mov_b32_e32 v83, v135
	s_cmp_gt_u32 s6, 10
	s_cselect_b64 exec, -1, 0
	v_fma_f32 v136, v72, v82, v136
	v_fma_f32 v137, v72, v83, v137
	v_fma_f32 v137, v74, v82, v137
	v_fma_f32 v82, -v74, v83, v136
	v_mov_b32_e32 v83, v137
	s_cmp_gt_u32 s6, 11
	s_cselect_b64 exec, -1, 0
	v_fma_f32 v138, v72, v82, v138
	v_fma_f32 v139, v72, v83, v139
	v_fma_f32 v139, v74, v82, v139
	v_fma_f32 v82, -v74, v83, v138
	v_mov_b32_e32 v83, v139
	s_cmp_gt_u32 s6, 12
	s_cselect_b64 exec, -1, 0
	v_fma_f32 v140, v72, v82, v140
	v_fma_f32 v141, v72, v83, v141
	v_fma_f32 v141, v74, v82, v141
	v_fma_f32 v82, -v74, v83, v140
	v_mov_b32_e32 v83, v141
	s_cmp_gt_u32 s6, 13
	s_cselect_b64 exec, -1, 0
	v_fma_f32 v142, v72, v82, v142
	v_fma_f32 v143, v72, v83, v143
	v_fma_f32 v143, v74, v82, v143
	v_fma_f32 v82, -v74, v83, v142
	v_mov_b32_e32 v83, v143
	s_cmp_gt_u32 s6, 14
	s_cselect_b64 exec, -1, 0
	v_fma_f32 v144, v72, v82, v144
	v_fma_f32 v145, v72, v83, v145
	v_fma_f32 v145, v74, v82, v145
	v_fma_f32 v82, -v74, v83, v144
	v_mov_b32_e32 v83, v145
	s_cmp_gt_u32 s6, 15
	s_cselect_b64 exec, -1, 0
	v_fma_f32 v146, v72, v82, v146
	v_fma_f32 v147, v72, v83, v147
	v_fma_f32 v147, v74, v82, v147
	v_fma_f32 v82, -v74, v83, v146
	v_mov_b32_e32 v83, v147
	s_cmp_le_u32 s6, 16
	s_cbranch_scc1 .Ls5f_cdone
	s_cmp_gt_u32 s6, 16
	s_cselect_b64 exec, -1, 0
	v_fma_f32 v148, v72, v82, v148
	v_fma_f32 v149, v72, v83, v149
	v_fma_f32 v149, v74, v82, v149
	v_fma_f32 v82, -v74, v83, v148
	v_mov_b32_e32 v83, v149
	s_cmp_gt_u32 s6, 17
	s_cselect_b64 exec, -1, 0
	v_fma_f32 v150, v72, v82, v150
	v_fma_f32 v151, v72, v83, v151
	v_fma_f32 v151, v74, v82, v151
	v_fma_f32 v82, -v74, v83, v150
	v_mov_b32_e32 v83, v151
	s_cmp_gt_u32 s6, 18
	s_cselect_b64 exec, -1, 0
	v_fma_f32 v152, v72, v82, v152
	v_fma_f32 v153, v72, v83, v153
	v_fma_f32 v153, v74, v82, v153
	v_fma_f32 v82, -v74, v83, v152
	v_mov_b32_e32 v83, v153
	s_cmp_gt_u32 s6, 19
	s_cselect_b64 exec, -1, 0
	v_fma_f32 v154, v72, v82, v154
	v_fma_f32 v155, v72, v83, v155
	v_fma_f32 v155, v74, v82, v155
	v_fma_f32 v82, -v74, v83, v154
	v_mov_b32_e32 v83, v155
	s_cmp_gt_u32 s6, 20
	s_cselect_b64 exec, -1, 0
	v_fma_f32 v156, v72, v82, v156
	v_fma_f32 v157, v72, v83, v157
	v_fma_f32 v157, v74, v82, v157
	v_fma_f32 v82, -v74, v83, v156
	v_mov_b32_e32 v83, v157
	s_cmp_gt_u32 s6, 21
	s_cselect_b64 exec, -1, 0
	v_fma_f32 v158, v72, v82, v158
	v_fma_f32 v159, v72, v83, v159
	v_fma_f32 v159, v74, v82, v159
	v_fma_f32 v82, -v74, v83, v158
	v_mov_b32_e32 v83, v159
	s_cmp_gt_u32 s6, 22
	s_cselect_b64 exec, -1, 0
	v_fma_f32 v160, v72, v82, v160
	v_fma_f32 v161, v72, v83, v161
	v_fma_f32 v161, v74, v82, v161
	v_fma_f32 v82, -v74, v83, v160
	v_mov_b32_e32 v83, v161
	s_cmp_gt_u32 s6, 23
	s_cselect_b64 exec, -1, 0
	v_fma_f32 v162, v72, v82, v162
	v_fma_f32 v163, v72, v83, v163
	v_fma_f32 v163, v74, v82, v163
	v_fma_f32 v82, -v74, v83, v162
	v_mov_b32_e32 v83, v163
	s_cmp_le_u32 s6, 24
	s_cbranch_scc1 .Ls5f_cdone
; template <bool FINAL>
; __device__ __forceinline__ void s5_wave(const Params& P, int j, int g, int idx0, int stride, char* ldsw) {
;     ...
;     for (; c + 8 <= chunk; c += 8) {
;       float2 e[8];
; #pragma unroll
;       for (int q = 0; q < 8; ++q) e[q] = hp[(size_t)(c + q) * 2048];
; #pragma unroll
;       for (int q = 0; q < 8; ++q) {
;         float t_r = pr * hr - pi * hi + e[q].x;
;         float t_i = pr * hi + pi * hr + e[q].y;
;         hr = t_r; hi = t_i;
;       }
;     }
	s_cmp_gt_u32 s6, 24
	s_cselect_b64 exec, -1, 0
	v_fma_f32 v164, v72, v82, v164
	v_fma_f32 v165, v72, v83, v165
	v_fma_f32 v165, v74, v82, v165
	v_fma_f32 v82, -v74, v83, v164
	v_mov_b32_e32 v83, v165
	s_cmp_gt_u32 s6, 25
	s_cselect_b64 exec, -1, 0
	v_fma_f32 v166, v72, v82, v166
	v_fma_f32 v167, v72, v83, v167
	v_fma_f32 v167, v74, v82, v167
	v_fma_f32 v82, -v74, v83, v166
	v_mov_b32_e32 v83, v167
	s_cmp_gt_u32 s6, 26
	s_cselect_b64 exec, -1, 0
	v_fma_f32 v168, v72, v82, v168
	v_fma_f32 v169, v72, v83, v169
	v_fma_f32 v169, v74, v82, v169
	v_fma_f32 v82, -v74, v83, v168
	v_mov_b32_e32 v83, v169
	s_cmp_gt_u32 s6, 27
	s_cselect_b64 exec, -1, 0
	v_fma_f32 v170, v72, v82, v170
	v_fma_f32 v171, v72, v83, v171
	v_fma_f32 v171, v74, v82, v171
	v_fma_f32 v82, -v74, v83, v170
	v_mov_b32_e32 v83, v171
	s_cmp_gt_u32 s6, 28
	s_cselect_b64 exec, -1, 0
	v_fma_f32 v172, v72, v82, v172
	v_fma_f32 v173, v72, v83, v173
	v_fma_f32 v173, v74, v82, v173
	v_fma_f32 v82, -v74, v83, v172
	v_mov_b32_e32 v83, v173
	s_cmp_gt_u32 s6, 29
	s_cselect_b64 exec, -1, 0
	v_fma_f32 v174, v72, v82, v174
	v_fma_f32 v175, v72, v83, v175
	v_fma_f32 v175, v74, v82, v175
	v_fma_f32 v82, -v74, v83, v174
	v_mov_b32_e32 v83, v175
	s_cmp_gt_u32 s6, 30
	s_cselect_b64 exec, -1, 0
	v_fma_f32 v176, v72, v82, v176
	v_fma_f32 v177, v72, v83, v177
	v_fma_f32 v177, v74, v82, v177
	v_fma_f32 v82, -v74, v83, v176
	v_mov_b32_e32 v83, v177
	s_cmp_gt_u32 s6, 31
	s_cselect_b64 exec, -1, 0
	v_fma_f32 v178, v72, v82, v178
	v_fma_f32 v179, v72, v83, v179
	v_fma_f32 v179, v74, v82, v179
	v_fma_f32 v82, -v74, v83, v178
	v_mov_b32_e32 v83, v179
	s_cmp_le_u32 s6, 32
	s_cbranch_scc1 .Ls5f_cdone
	s_cmp_gt_u32 s6, 32
	s_cselect_b64 exec, -1, 0
	global_load_dwordx2 v[116:117], v109, s[14:15]
	s_mov_b64 exec, -1
	v_add_u32_e32 v109, 0x4000, v109
	s_cmp_gt_u32 s6, 33
	s_cselect_b64 exec, -1, 0
	global_load_dwordx2 v[118:119], v109, s[14:15]
	s_mov_b64 exec, -1
	v_add_u32_e32 v109, 0x4000, v109
	s_cmp_gt_u32 s6, 34
	s_cselect_b64 exec, -1, 0
	global_load_dwordx2 v[120:121], v109, s[14:15]
	s_mov_b64 exec, -1
	v_add_u32_e32 v109, 0x4000, v109
	s_cmp_gt_u32 s6, 35
	s_cselect_b64 exec, -1, 0
	global_load_dwordx2 v[122:123], v109, s[14:15]
	s_mov_b64 exec, -1
	v_add_u32_e32 v109, 0x4000, v109
	s_cmp_gt_u32 s6, 36
	s_cselect_b64 exec, -1, 0
	global_load_dwordx2 v[124:125], v109, s[14:15]
	s_mov_b64 exec, -1
	v_add_u32_e32 v109, 0x4000, v109
	s_cmp_gt_u32 s6, 37
	s_cselect_b64 exec, -1, 0
	global_load_dwordx2 v[126:127], v109, s[14:15]
	s_mov_b64 exec, -1
	v_add_u32_e32 v109, 0x4000, v109
	s_cmp_gt_u32 s6, 38
	s_cselect_b64 exec, -1, 0
	global_load_dwordx2 v[128:129], v109, s[14:15]
	s_mov_b64 exec, -1
	v_add_u32_e32 v109, 0x4000, v109
	s_cmp_gt_u32 s6, 39
	s_cselect_b64 exec, -1, 0
	global_load_dwordx2 v[130:131], v109, s[14:15]
	s_mov_b64 exec, -1
	v_add_u32_e32 v109, 0x4000, v109
	s_cmp_gt_u32 s6, 40
	s_cselect_b64 exec, -1, 0
	global_load_dwordx2 v[132:133], v109, s[14:15]
	s_mov_b64 exec, -1
	v_add_u32_e32 v109, 0x4000, v109
	s_cmp_gt_u32 s6, 41
	s_cselect_b64 exec, -1, 0
	global_load_dwordx2 v[134:135], v109, s[14:15]
	s_mov_b64 exec, -1
	v_add_u32_e32 v109, 0x4000, v109
	s_cmp_gt_u32 s6, 42
	s_cselect_b64 exec, -1, 0
	global_load_dwordx2 v[136:137], v109, s[14:15]
	s_mov_b64 exec, -1
	v_add_u32_e32 v109, 0x4000, v109
	s_cmp_gt_u32 s6, 43
	s_cselect_b64 exec, -1, 0
	global_load_dwordx2 v[138:139], v109, s[14:15]
	s_mov_b64 exec, -1
	v_add_u32_e32 v109, 0x4000, v109
	s_cmp_gt_u32 s6, 44
	s_cselect_b64 exec, -1, 0
	global_load_dwordx2 v[140:141], v109, s[14:15]
	s_mov_b64 exec, -1
	v_add_u32_e32 v109, 0x4000, v109
	s_cmp_gt_u32 s6, 45
	s_cselect_b64 exec, -1, 0
	global_load_dwordx2 v[142:143], v109, s[14:15]
	s_mov_b64 exec, -1
	v_add_u32_e32 v109, 0x4000, v109
	s_cmp_gt_u32 s6, 46
	s_cselect_b64 exec, -1, 0
	global_load_dwordx2 v[144:145], v109, s[14:15]
	s_mov_b64 exec, -1
	v_add_u32_e32 v109, 0x4000, v109
	s_cmp_gt_u32 s6, 47
	s_cselect_b64 exec, -1, 0
	global_load_dwordx2 v[146:147], v109, s[14:15]
	s_mov_b64 exec, -1
	v_add_u32_e32 v109, 0x4000, v109
	s_cmp_gt_u32 s6, 48
	s_cselect_b64 exec, -1, 0
	global_load_dwordx2 v[148:149], v109, s[14:15]
	s_mov_b64 exec, -1
	v_add_u32_e32 v109, 0x4000, v109
	s_cmp_gt_u32 s6, 49
	s_cselect_b64 exec, -1, 0
	global_load_dwordx2 v[150:151], v109, s[14:15]
	s_mov_b64 exec, -1
	v_add_u32_e32 v109, 0x4000, v109
	s_cmp_gt_u32 s6, 50
	s_cselect_b64 exec, -1, 0
	global_load_dwordx2 v[152:153], v109, s[14:15]
	s_mov_b64 exec, -1
	v_add_u32_e32 v109, 0x4000, v109
	s_cmp_gt_u32 s6, 51
	s_cselect_b64 exec, -1, 0
	global_load_dwordx2 v[154:155], v109, s[14:15]
	s_mov_b64 exec, -1
	v_add_u32_e32 v109, 0x4000, v109
	s_cmp_gt_u32 s6, 52
	s_cselect_b64 exec, -1, 0
	global_load_dwordx2 v[156:157], v109, s[14:15]
	s_mov_b64 exec, -1
	v_add_u32_e32 v109, 0x4000, v109
	s_cmp_gt_u32 s6, 53
	s_cselect_b64 exec, -1, 0
	global_load_dwordx2 v[158:159], v109, s[14:15]
	s_mov_b64 exec, -1
	v_add_u32_e32 v109, 0x4000, v109
	s_cmp_gt_u32 s6, 54
	s_cselect_b64 exec, -1, 0
	global_load_dwordx2 v[160:161], v109, s[14:15]
	s_mov_b64 exec, -1
	v_add_u32_e32 v109, 0x4000, v109
	s_cmp_gt_u32 s6, 55
	s_cselect_b64 exec, -1, 0
	global_load_dwordx2 v[162:163], v109, s[14:15]
	s_mov_b64 exec, -1
	v_add_u32_e32 v109, 0x4000, v109
	s_cmp_gt_u32 s6, 56
	s_cselect_b64 exec, -1, 0
	global_load_dwordx2 v[164:165], v109, s[14:15]
	s_mov_b64 exec, -1
	v_add_u32_e32 v109, 0x4000, v109
	s_cmp_gt_u32 s6, 57
	s_cselect_b64 exec, -1, 0
	global_load_dwordx2 v[166:167], v109, s[14:15]
	s_mov_b64 exec, -1
	v_add_u32_e32 v109, 0x4000, v109
	s_cmp_gt_u32 s6, 58
	s_cselect_b64 exec, -1, 0
	global_load_dwordx2 v[168:169], v109, s[14:15]
	s_mov_b64 exec, -1
	v_add_u32_e32 v109, 0x4000, v109
	s_cmp_gt_u32 s6, 59
	s_cselect_b64 exec, -1, 0
	global_load_dwordx2 v[170:171], v109, s[14:15]
	s_mov_b64 exec, -1
	v_add_u32_e32 v109, 0x4000, v109
	s_cmp_gt_u32 s6, 60
	s_cselect_b64 exec, -1, 0
	global_load_dwordx2 v[172:173], v109, s[14:15]
	s_mov_b64 exec, -1
	v_add_u32_e32 v109, 0x4000, v109
	s_cmp_gt_u32 s6, 61
	s_cselect_b64 exec, -1, 0
	global_load_dwordx2 v[174:175], v109, s[14:15]
	s_mov_b64 exec, -1
	v_add_u32_e32 v109, 0x4000, v109
	s_cmp_gt_u32 s6, 62
	s_cselect_b64 exec, -1, 0
	global_load_dwordx2 v[176:177], v109, s[14:15]
	s_mov_b64 exec, -1
	v_add_u32_e32 v109, 0x4000, v109
	s_cmp_gt_u32 s6, 63
	s_cselect_b64 exec, -1, 0
	global_load_dwordx2 v[178:179], v109, s[14:15]
	s_mov_b64 exec, -1
	v_add_u32_e32 v109, 0x4000, v109
	s_waitcnt vmcnt(0)
; template <bool FINAL>
; __device__ __forceinline__ void s5_wave(const Params& P, int j, int g, int idx0, int stride, char* ldsw) {
;     ...
;     for (; c + 8 <= chunk; c += 8) {
;       float2 e[8];
; #pragma unroll
;       for (int q = 0; q < 8; ++q) e[q] = hp[(size_t)(c + q) * 2048];
; #pragma unroll
;       for (int q = 0; q < 8; ++q) {
;         float t_r = pr * hr - pi * hi + e[q].x;
;         float t_i = pr * hi + pi * hr + e[q].y;
;         hr = t_r; hi = t_i;
;       }
;     }
;     for (; c < chunk; ++c) {
;       float2 e = hp[(size_t)c * 2048];
;       float t_r = pr * hr - pi * hi + e.x;
;       float t_i = pr * hi + pi * hr + e.y;
;       hr = t_r; hi = t_i;
;     }
	s_cmp_gt_u32 s6, 32
	s_cselect_b64 exec, -1, 0
	v_fma_f32 v116, v72, v82, v116
	v_fma_f32 v117, v72, v83, v117
	v_fma_f32 v117, v74, v82, v117
	v_fma_f32 v82, -v74, v83, v116
	v_mov_b32_e32 v83, v117
	s_cmp_gt_u32 s6, 33
	s_cselect_b64 exec, -1, 0
	v_fma_f32 v118, v72, v82, v118
	v_fma_f32 v119, v72, v83, v119
	v_fma_f32 v119, v74, v82, v119
	v_fma_f32 v82, -v74, v83, v118
	v_mov_b32_e32 v83, v119
	s_cmp_gt_u32 s6, 34
	s_cselect_b64 exec, -1, 0
	v_fma_f32 v120, v72, v82, v120
	v_fma_f32 v121, v72, v83, v121
	v_fma_f32 v121, v74, v82, v121
	v_fma_f32 v82, -v74, v83, v120
	v_mov_b32_e32 v83, v121
	s_cmp_gt_u32 s6, 35
	s_cselect_b64 exec, -1, 0
	v_fma_f32 v122, v72, v82, v122
	v_fma_f32 v123, v72, v83, v123
	v_fma_f32 v123, v74, v82, v123
	v_fma_f32 v82, -v74, v83, v122
	v_mov_b32_e32 v83, v123
	s_cmp_gt_u32 s6, 36
	s_cselect_b64 exec, -1, 0
	v_fma_f32 v124, v72, v82, v124
	v_fma_f32 v125, v72, v83, v125
	v_fma_f32 v125, v74, v82, v125
	v_fma_f32 v82, -v74, v83, v124
	v_mov_b32_e32 v83, v125
	s_cmp_gt_u32 s6, 37
	s_cselect_b64 exec, -1, 0
	v_fma_f32 v126, v72, v82, v126
	v_fma_f32 v127, v72, v83, v127
	v_fma_f32 v127, v74, v82, v127
	v_fma_f32 v82, -v74, v83, v126
	v_mov_b32_e32 v83, v127
	s_cmp_gt_u32 s6, 38
	s_cselect_b64 exec, -1, 0
	v_fma_f32 v128, v72, v82, v128
	v_fma_f32 v129, v72, v83, v129
	v_fma_f32 v129, v74, v82, v129
	v_fma_f32 v82, -v74, v83, v128
	v_mov_b32_e32 v83, v129
	s_cmp_gt_u32 s6, 39
	s_cselect_b64 exec, -1, 0
	v_fma_f32 v130, v72, v82, v130
	v_fma_f32 v131, v72, v83, v131
	v_fma_f32 v131, v74, v82, v131
	v_fma_f32 v82, -v74, v83, v130
	v_mov_b32_e32 v83, v131
	s_cmp_le_u32 s6, 40
	s_cbranch_scc1 .Ls5f_cdone
	s_cmp_gt_u32 s6, 40
	s_cselect_b64 exec, -1, 0
	v_fma_f32 v132, v72, v82, v132
	v_fma_f32 v133, v72, v83, v133
	v_fma_f32 v133, v74, v82, v133
	v_fma_f32 v82, -v74, v83, v132
	v_mov_b32_e32 v83, v133
	s_cmp_gt_u32 s6, 41
	s_cselect_b64 exec, -1, 0
	v_fma_f32 v134, v72, v82, v134
	v_fma_f32 v135, v72, v83, v135
	v_fma_f32 v135, v74, v82, v135
	v_fma_f32 v82, -v74, v83, v134
	v_mov_b32_e32 v83, v135
	s_cmp_gt_u32 s6, 42
	s_cselect_b64 exec, -1, 0
	v_fma_f32 v136, v72, v82, v136
	v_fma_f32 v137, v72, v83, v137
	v_fma_f32 v137, v74, v82, v137
	v_fma_f32 v82, -v74, v83, v136
	v_mov_b32_e32 v83, v137
	s_cmp_gt_u32 s6, 43
	s_cselect_b64 exec, -1, 0
	v_fma_f32 v138, v72, v82, v138
	v_fma_f32 v139, v72, v83, v139
	v_fma_f32 v139, v74, v82, v139
	v_fma_f32 v82, -v74, v83, v138
	v_mov_b32_e32 v83, v139
	s_cmp_gt_u32 s6, 44
	s_cselect_b64 exec, -1, 0
	v_fma_f32 v140, v72, v82, v140
	v_fma_f32 v141, v72, v83, v141
	v_fma_f32 v141, v74, v82, v141
	v_fma_f32 v82, -v74, v83, v140
	v_mov_b32_e32 v83, v141
	s_cmp_gt_u32 s6, 45
	s_cselect_b64 exec, -1, 0
	v_fma_f32 v142, v72, v82, v142
	v_fma_f32 v143, v72, v83, v143
	v_fma_f32 v143, v74, v82, v143
	v_fma_f32 v82, -v74, v83, v142
	v_mov_b32_e32 v83, v143
	s_cmp_gt_u32 s6, 46
	s_cselect_b64 exec, -1, 0
	v_fma_f32 v144, v72, v82, v144
	v_fma_f32 v145, v72, v83, v145
	v_fma_f32 v145, v74, v82, v145
	v_fma_f32 v82, -v74, v83, v144
	v_mov_b32_e32 v83, v145
	s_cmp_gt_u32 s6, 47
	s_cselect_b64 exec, -1, 0
	v_fma_f32 v146, v72, v82, v146
	v_fma_f32 v147, v72, v83, v147
	v_fma_f32 v147, v74, v82, v147
	v_fma_f32 v82, -v74, v83, v146
	v_mov_b32_e32 v83, v147
	s_cmp_le_u32 s6, 48
	s_cbranch_scc1 .Ls5f_cdone
	s_cmp_gt_u32 s6, 48
	s_cselect_b64 exec, -1, 0
	v_fma_f32 v148, v72, v82, v148
	v_fma_f32 v149, v72, v83, v149
	v_fma_f32 v149, v74, v82, v149
	v_fma_f32 v82, -v74, v83, v148
	v_mov_b32_e32 v83, v149
	s_cmp_gt_u32 s6, 49
	s_cselect_b64 exec, -1, 0
	v_fma_f32 v150, v72, v82, v150
	v_fma_f32 v151, v72, v83, v151
	v_fma_f32 v151, v74, v82, v151
	v_fma_f32 v82, -v74, v83, v150
	v_mov_b32_e32 v83, v151
	s_cmp_gt_u32 s6, 50
	s_cselect_b64 exec, -1, 0
	v_fma_f32 v152, v72, v82, v152
	v_fma_f32 v153, v72, v83, v153
	v_fma_f32 v153, v74, v82, v153
	v_fma_f32 v82, -v74, v83, v152
	v_mov_b32_e32 v83, v153
	s_cmp_gt_u32 s6, 51
	s_cselect_b64 exec, -1, 0
	v_fma_f32 v154, v72, v82, v154
	v_fma_f32 v155, v72, v83, v155
	v_fma_f32 v155, v74, v82, v155
	v_fma_f32 v82, -v74, v83, v154
	v_mov_b32_e32 v83, v155
	s_cmp_gt_u32 s6, 52
	s_cselect_b64 exec, -1, 0
	v_fma_f32 v156, v72, v82, v156
	v_fma_f32 v157, v72, v83, v157
	v_fma_f32 v157, v74, v82, v157
	v_fma_f32 v82, -v74, v83, v156
	v_mov_b32_e32 v83, v157
	s_cmp_gt_u32 s6, 53
	s_cselect_b64 exec, -1, 0
	v_fma_f32 v158, v72, v82, v158
	v_fma_f32 v159, v72, v83, v159
	v_fma_f32 v159, v74, v82, v159
	v_fma_f32 v82, -v74, v83, v158
	v_mov_b32_e32 v83, v159
	s_cmp_gt_u32 s6, 54
	s_cselect_b64 exec, -1, 0
	v_fma_f32 v160, v72, v82, v160
	v_fma_f32 v161, v72, v83, v161
	v_fma_f32 v161, v74, v82, v161
	v_fma_f32 v82, -v74, v83, v160
	v_mov_b32_e32 v83, v161
	s_cmp_gt_u32 s6, 55
	s_cselect_b64 exec, -1, 0
	v_fma_f32 v162, v72, v82, v162
	v_fma_f32 v163, v72, v83, v163
	v_fma_f32 v163, v74, v82, v163
	v_fma_f32 v82, -v74, v83, v162
	v_mov_b32_e32 v83, v163
	s_cmp_le_u32 s6, 56
	s_cbranch_scc1 .Ls5f_cdone
	s_cmp_gt_u32 s6, 56
	s_cselect_b64 exec, -1, 0
	v_fma_f32 v164, v72, v82, v164
	v_fma_f32 v165, v72, v83, v165
	v_fma_f32 v165, v74, v82, v165
	v_fma_f32 v82, -v74, v83, v164
	v_mov_b32_e32 v83, v165
	s_cmp_gt_u32 s6, 57
	s_cselect_b64 exec, -1, 0
	v_fma_f32 v166, v72, v82, v166
	v_fma_f32 v167, v72, v83, v167
	v_fma_f32 v167, v74, v82, v167
	v_fma_f32 v82, -v74, v83, v166
	v_mov_b32_e32 v83, v167
	s_cmp_gt_u32 s6, 58
	s_cselect_b64 exec, -1, 0
	v_fma_f32 v168, v72, v82, v168
	v_fma_f32 v169, v72, v83, v169
	v_fma_f32 v169, v74, v82, v169
	v_fma_f32 v82, -v74, v83, v168
	v_mov_b32_e32 v83, v169
	s_cmp_gt_u32 s6, 59
	s_cselect_b64 exec, -1, 0
	v_fma_f32 v170, v72, v82, v170
	v_fma_f32 v171, v72, v83, v171
	v_fma_f32 v171, v74, v82, v171
	v_fma_f32 v82, -v74, v83, v170
	v_mov_b32_e32 v83, v171
	s_cmp_gt_u32 s6, 60
	s_cselect_b64 exec, -1, 0
	v_fma_f32 v172, v72, v82, v172
	v_fma_f32 v173, v72, v83, v173
	v_fma_f32 v173, v74, v82, v173
	v_fma_f32 v82, -v74, v83, v172
	v_mov_b32_e32 v83, v173
	s_cmp_gt_u32 s6, 61
	s_cselect_b64 exec, -1, 0
	v_fma_f32 v174, v72, v82, v174
	v_fma_f32 v175, v72, v83, v175
	v_fma_f32 v175, v74, v82, v175
	v_fma_f32 v82, -v74, v83, v174
	v_mov_b32_e32 v83, v175
	s_cmp_gt_u32 s6, 62
	s_cselect_b64 exec, -1, 0
	v_fma_f32 v176, v72, v82, v176
	v_fma_f32 v177, v72, v83, v177
	v_fma_f32 v177, v74, v82, v177
	v_fma_f32 v82, -v74, v83, v176
	v_mov_b32_e32 v83, v177
	s_cmp_gt_u32 s6, 63
	s_cselect_b64 exec, -1, 0
	v_fma_f32 v178, v72, v82, v178
	v_fma_f32 v179, v72, v83, v179
	v_fma_f32 v179, v74, v82, v179
	v_fma_f32 v82, -v74, v83, v178
	v_mov_b32_e32 v83, v179
.Ls5f_cdone:
	s_mov_b64 exec, -1
